# k/v up-projection epilogue: k-norm gain vector parked in LDS once per phase (ds_read instead of two global loads + vmcnt(0) after the exchange barrier); header comment updated
# speedup vs baseline: 1.0074x; 1.0074x over previous
; #define PG8_STAGE(bufoff, gbase, voff) do { _Pragma("unroll") for (int _i = 0; _i < 2; ++_i) \
;         __builtin_amdgcn_global_load_lds((const unsigned*)((const char*)(gbase) + (voff)[_i]), (PG8_LAS unsigned*)(lds + (bufoff) + ldsw + _i * 8192), 16, 0, 0); } while (0)
; #define PG8_WAIT_V(n) asm volatile("s_waitcnt vmcnt(" #n ")" ::: "memory")
; #define PG8_BAR __builtin_amdgcn_s_barrier()
;     __device__ __forceinline__ void operator()(const f32x4 (&acc)[2][2][4][2], const Unit& u, int wr, int wc, int fr, int fq) const {
;     ...
;         const int colh = wc * 32 + 8 * fq;
;         const f32x4 g0 = *(const f32x4*)(g + colh), g1 = *(const f32x4*)(g + colh + 4);
;         const int head0 = colt >> 7;
;         bf16_t* base = Kn + colh;
; template <class Epi, class Sched, bool ALIGN_EPI = false, bool SP2 = false>
; __device__ __forceinline__ void gemm_phase(PG8_LAS unsigned char* lds, const Gemm g, const Sched& S, const Epi& E) {
;     ...
;         PG8_STAGE(PG8_SB(0, 0), cB, voffB); PG8_STAGE(PG8_SB(0, 1), cB + hstep, voffB); PG8_STAGE(PG8_SA(0, 0), cA, voffA); PG8_STAGE(PG8_SA(0, 1), cA + hstep, voffA);
;         if (wr == 1) PG8_BAR;
;         PG8_WAIT_V(2); PG8_BAR;
;         PG8_STAGE(PG8_SB(1, 0), cB + kstep, voffB); PG8_STAGE(PG8_SA(1, 0), cA + kstep, voffA); PG8_STAGE(PG8_SB(1, 1), cB + hstep + kstep, voffB);
;         PG8_WAIT_V(6); PG8_BAR;
.LBB0_749:
	s_and_b32 s50, s3, 3
	s_add_i32 m0, s80, 0x18000
	v_lshl_add_u64 v[10:11], v[10:11], 0, s[28:29]
	s_lshl_b32 s3, s46, 13
	s_lshl_b32 s47, s50, 12
	s_waitcnt vmcnt(2)
	s_barrier
	global_load_lds_dwordx4 v[10:11], off
	v_lshl_add_u64 v[8:9], v[8:9], 0, s[28:29]
	s_add_i32 m0, s80, 0x1a000
	s_add_i32 s84, s80, 0x8000
	s_add_i32 s85, s80, 0xa000
	global_load_lds_dwordx4 v[8:9], off
	v_lshl_add_u64 v[4:5], v[4:5], 0, s[28:29]
	s_mov_b32 m0, s84
	s_add_u32 s42, s66, 0x20080
	global_load_lds_dwordx4 v[4:5], off
	v_lshl_add_u64 v[4:5], v[6:7], 0, s[28:29]
	s_mov_b32 m0, s85
	s_addc_u32 s43, s67, 0
	global_load_lds_dwordx4 v[4:5], off
	s_add_i32 m0, s80, 0x1c000
	v_lshl_add_u64 v[4:5], s[42:43], 0, v[2:3]
	global_load_lds_dwordx4 v[4:5], off
	v_lshl_add_u64 v[4:5], s[42:43], 0, v[144:145]
	s_add_i32 m0, s80, 0x1e000
	v_bfe_u32 v6, v17, 4, 2
	global_load_lds_dwordx4 v[4:5], off
	v_and_b32_e32 v5, 15, v17
	v_lshlrev_b32_e32 v4, 4, v6
	s_cmpk_lt_u32 s2, 0x100
	v_lshl_or_b32 v161, s46, 6, v5
	v_lshl_or_b32 v8, v5, 6, v4
	v_lshlrev_b32_e32 v5, 2, v5
	s_cselect_b64 s[42:43], -1, 0
	s_lshl_b32 s52, s46, 12
	s_lshl_b32 s53, s50, 10
	v_and_b32_e32 v9, 32, v5
	s_cmpk_gt_u32 s70, 0x57
	v_bitop3_b32 v162, v8, s47, v9 bitop3:0xde
	s_cselect_b64 s[46:47], -1, 0
	s_cmpk_lt_u32 s70, 0xd0
	s_cselect_b64 s[48:49], -1, 0
	s_add_i32 s52, s52, 0
	v_lshlrev_b32_e32 v7, 3, v6
	s_add_i32 s52, s52, 0x20400
	v_bitop3_b32 v10, v8, s3, v9 bitop3:0xde
	v_lshl_or_b32 v8, s50, 5, v7
	s_add_i32 s86, s70, 0xb50
	s_add_i32 s87, s70, 0xaa8
	s_add_i32 s88, s70, 0x1c0
	s_add_i32 s53, s52, s53
	s_lshl_b32 s50, s50, 6
	v_add_u32_e32 v172, s52, v5
	s_add_u32 s52, s19, s50
	v_add_u32_e32 v163, s53, v5
	s_addc_u32 s53, s79, 0
	v_mov_b32_e32 v5, v3
	v_lshl_add_u64 v[150:151], s[52:53], 0, v[4:5]
	v_lshlrev_b32_e32 v4, 13, v12
	v_and_b32_e32 v4, 0xffffc000, v4
	v_lshl_add_u32 v4, v13, 10, v4
	v_and_b32_e32 v5, 1, v12
	v_lshl_or_b32 v4, v5, 6, v4
	v_lshl_add_u32 v152, v14, 1, v4
	v_lshlrev_b32_e32 v4, 13, v15
	v_and_b32_e32 v4, 0xffffc000, v4
	s_waitcnt vmcnt(6)
	v_cmp_eq_u32_e64 s[2:3], 0, v6
	v_lshlrev_b32_e32 v6, 2, v8
	v_mov_b32_e32 v7, v3
	v_lshl_add_u32 v4, v16, 10, v4
	v_and_b32_e32 v5, 1, v15
	v_lshl_add_u64 v[146:147], s[36:37], 0, v[6:7]
	global_load_dwordx4 v[20:23], v[146:147], off offset:16
	global_load_dwordx4 v[24:27], v[146:147], off
	v_add_u32_e32 v146, 0x23500, v6
	s_waitcnt vmcnt(0)
	ds_write_b128 v146, v[20:23] offset:16
	ds_write_b128 v146, v[24:27]
	s_waitcnt lgkmcnt(0)
	v_lshlrev_b32_e32 v6, 1, v8
	v_lshl_or_b32 v4, v5, 6, v4
	s_mov_b32 s51, 0
	v_lshl_add_u64 v[148:149], s[4:5], 0, v[6:7]
	v_mov_b32_e32 v153, v3
	v_lshl_add_u32 v154, v18, 1, v4
	v_mov_b32_e32 v155, v3
	v_add_u32_e32 v173, 0, v10
	s_barrier
	s_branch .LBB0_752

; __device__ __forceinline__ unsigned cvtpk(float lo, float hi) { unsigned r; asm volatile("v_cvt_pk_bf16_f32 %0, %1, %2" : "=v"(r) : "v"(lo), "v"(hi)); return r; }
;     __device__ __forceinline__ void operator()(const f32x4 (&acc)[2][2][4][2], const Unit& u, int wr, int wc, int fr, int fq) const {
;     ...
;         asm volatile("s_waitcnt lgkmcnt(0)" ::: "memory"); __builtin_amdgcn_s_barrier(); asm volatile("" ::: "memory");
;         const int colh = wc * 32 + 8 * fq;
;         const f32x4 g0 = *(const f32x4*)(g + colh), g1 = *(const f32x4*)(g + colh + 4);
;         const int head0 = colt >> 7;
;         bf16_t* base = Kn + colh;
; #pragma unroll
;         for (int ai = 0; ai < 2; ++ai)
; #pragma unroll
;             for (int m = 0; m < 4; ++m) { const size_t r = (size_t)(row0 + ai * HALF + m * 16);
; #pragma unroll
;                 for (int bj = 0; bj < 2; ++bj) {
;                     const int slot = ((ai * 4 + m) * 2 + bj) * 16 + fr;
;                     const float tot = (xl[(wr * 4 + 0) * 256 + slot] + xl[(wr * 4 + 1) * 256 + slot]) + (xl[(wr * 4 + 2) * 256 + slot] + xl[(wr * 4 + 3) * 256 + slot]);
;                     const float rs = rsqrtf(tot * (1.f / 128) + NORM_EPS);
;                     const f32x4 v0 = acc[ai][bj][m][0] * rs * g0, v1 = acc[ai][bj][m][1] * rs * g1;
;                     u32x4 w; w.x = cvtpk(v0[0], v0[1]); w.y = cvtpk(v0[2], v0[3]); w.z = cvtpk(v1[0], v1[1]); w.w = cvtpk(v1[2], v1[3]);
;                     *(u32x4*)(base + ((size_t)(head0 + bj) * KROWS + r) * 128) = w; } }
.LBB0_771:
	s_or_b64 exec, exec, s[62:63]
	s_waitcnt lgkmcnt(0)
	s_barrier
	s_waitcnt lgkmcnt(0)
	ds_read_b128 v[132:135], v146 offset:16
	ds_read_b128 v[136:139], v146
	ds_read2st64_b32 v[158:159], v172 offset1:4
	ds_read2st64_b32 v[164:165], v172 offset0:8 offset1:12
	s_lshl_b32 s51, s54, 1
	v_ashrrev_i32_e32 v157, 31, v156
	s_or_b32 s53, s51, 1
	s_waitcnt lgkmcnt(0)
	v_mov_b32_e32 v174, v158
	v_mov_b32_e32 v175, v164
	v_mov_b32_e32 v164, v159
	v_pk_add_f32 v[158:159], v[174:175], v[164:165]
	s_nop 0
	v_add_f32_e32 v158, v158, v159
	v_fmamk_f32 v158, v158, 0x3c000000, v1
	v_cmp_gt_f32_e32 vcc, s33, v158
	v_mul_f32_e32 v159, 0x4b800000, v158
	s_nop 0
	v_cndmask_b32_e32 v158, v158, v159, vcc
	v_rsq_f32_e32 v158, v158
	s_nop 0
	v_mul_f32_e32 v159, 0x45800000, v158
	v_cndmask_b32_e32 v158, v158, v159, vcc
	v_pk_mul_f32 v[174:175], v[130:131], v[158:159] op_sel_hi:[1,0]
	v_pk_mul_f32 v[164:165], v[128:129], v[158:159] op_sel_hi:[1,0]
	v_pk_mul_f32 v[176:177], v[138:139], v[174:175]
	v_pk_mul_f32 v[174:175], v[124:125], v[158:159] op_sel_hi:[1,0]
	v_pk_mul_f32 v[158:159], v[126:127], v[158:159] op_sel_hi:[1,0]
	v_pk_mul_f32 v[164:165], v[136:137], v[164:165]
	v_pk_mul_f32 v[158:159], v[134:135], v[158:159]
	v_pk_mul_f32 v[178:179], v[132:133], v[174:175]
	v_cvt_pk_bf16_f32 v174, v164, v165
	v_cvt_pk_bf16_f32 v175, v176, v177
	s_nop 0
	v_cvt_pk_bf16_f32 v176, v178, v179
	v_cvt_pk_bf16_f32 v177, v158, v159
	v_mad_i64_i32 v[158:159], s[62:63], s51, v203, v[156:157]
	v_lshlrev_b64 v[158:159], 8, v[158:159]
	v_lshl_add_u64 v[158:159], v[148:149], 0, v[158:159]
	global_store_dwordx4 v[158:159], v[174:177], off
	s_nop 1
	v_add_u32_e32 v174, 64, v172
	ds_read2st64_b32 v[158:159], v174 offset1:4
	ds_read2st64_b32 v[164:165], v174 offset0:8 offset1:12
	v_add_u32_e32 v175, 0xc0, v172
	s_waitcnt lgkmcnt(1)
	v_mov_b32_e32 v176, v158
	s_waitcnt lgkmcnt(0)
	v_mov_b32_e32 v177, v164
	v_mov_b32_e32 v164, v159
	v_pk_add_f32 v[158:159], v[176:177], v[164:165]
	s_nop 0
	v_add_f32_e32 v158, v158, v159
	v_fmamk_f32 v158, v158, 0x3c000000, v1
	v_cmp_gt_f32_e32 vcc, s33, v158
	v_mul_f32_e32 v159, 0x4b800000, v158
	s_nop 0
	v_cndmask_b32_e32 v158, v158, v159, vcc
	v_rsq_f32_e32 v158, v158
	s_nop 0
	v_mul_f32_e32 v159, 0x45800000, v158
	v_cndmask_b32_e32 v158, v158, v159, vcc
	v_pk_mul_f32 v[176:177], v[122:123], v[158:159] op_sel_hi:[1,0]
	v_pk_mul_f32 v[164:165], v[120:121], v[158:159] op_sel_hi:[1,0]
	v_pk_mul_f32 v[178:179], v[138:139], v[176:177]
	v_pk_mul_f32 v[176:177], v[112:113], v[158:159] op_sel_hi:[1,0]
	v_pk_mul_f32 v[158:159], v[114:115], v[158:159] op_sel_hi:[1,0]
	v_pk_mul_f32 v[164:165], v[136:137], v[164:165]
	v_pk_mul_f32 v[158:159], v[134:135], v[158:159]
	v_pk_mul_f32 v[180:181], v[132:133], v[176:177]
	v_cvt_pk_bf16_f32 v176, v164, v165
	v_cvt_pk_bf16_f32 v177, v178, v179
	s_nop 0
	v_cvt_pk_bf16_f32 v178, v180, v181
	v_cvt_pk_bf16_f32 v179, v158, v159
	v_mad_i64_i32 v[158:159], s[62:63], s53, v203, v[156:157]
	v_lshlrev_b64 v[158:159], 8, v[158:159]
	v_lshl_add_u64 v[158:159], v[148:149], 0, v[158:159]
	global_store_dwordx4 v[158:159], v[176:179], off
	v_add_u32_e32 v157, 0x80, v172
	ds_read2st64_b32 v[164:165], v157 offset1:4
	ds_read2st64_b32 v[176:177], v157 offset0:8 offset1:12
	v_or_b32_e32 v158, 16, v156
	v_ashrrev_i32_e32 v159, 31, v158
	s_waitcnt lgkmcnt(1)
	v_mov_b32_e32 v178, v164
	s_waitcnt lgkmcnt(0)
	v_mov_b32_e32 v179, v176
	v_mov_b32_e32 v176, v165
	v_pk_add_f32 v[164:165], v[178:179], v[176:177]
	s_nop 0
	v_add_f32_e32 v164, v164, v165
	v_fmamk_f32 v164, v164, 0x3c000000, v1
	v_cmp_gt_f32_e32 vcc, s33, v164
	v_mul_f32_e32 v165, 0x4b800000, v164
	s_nop 0
	v_cndmask_b32_e32 v164, v164, v165, vcc
	v_rsq_f32_e32 v164, v164
	s_nop 0
	v_mul_f32_e32 v165, 0x45800000, v164
	v_cndmask_b32_e32 v164, v164, v165, vcc
	v_pk_mul_f32 v[176:177], v[116:117], v[164:165] op_sel_hi:[1,0]
	v_pk_mul_f32 v[178:179], v[118:119], v[164:165] op_sel_hi:[1,0]
	v_pk_mul_f32 v[180:181], v[108:109], v[164:165] op_sel_hi:[1,0]
	v_pk_mul_f32 v[164:165], v[110:111], v[164:165] op_sel_hi:[1,0]
	v_pk_mul_f32 v[178:179], v[138:139], v[178:179]
	v_pk_mul_f32 v[176:177], v[136:137], v[176:177]
	v_pk_mul_f32 v[164:165], v[134:135], v[164:165]
	v_pk_mul_f32 v[180:181], v[132:133], v[180:181]
	v_cvt_pk_bf16_f32 v176, v176, v177
	v_cvt_pk_bf16_f32 v177, v178, v179
	s_nop 0
	v_cvt_pk_bf16_f32 v178, v180, v181
	v_cvt_pk_bf16_f32 v179, v164, v165
	v_mad_i64_i32 v[164:165], s[62:63], s51, v203, v[158:159]
	v_lshlrev_b64 v[164:165], 8, v[164:165]
	v_lshl_add_u64 v[164:165], v[148:149], 0, v[164:165]
	global_store_dwordx4 v[164:165], v[176:179], off
	ds_read2st64_b32 v[164:165], v175 offset1:4
	ds_read2st64_b32 v[176:177], v175 offset0:8 offset1:12
	v_mad_i64_i32 v[158:159], s[62:63], s53, v203, v[158:159]
	v_lshlrev_b64 v[158:159], 8, v[158:159]
	s_waitcnt lgkmcnt(1)
	v_mov_b32_e32 v178, v164
	s_waitcnt lgkmcnt(0)
	v_mov_b32_e32 v179, v176
	v_mov_b32_e32 v176, v165
	v_pk_add_f32 v[164:165], v[178:179], v[176:177]
	v_lshl_add_u64 v[158:159], v[148:149], 0, v[158:159]
	v_add_f32_e32 v164, v164, v165
	v_fmamk_f32 v164, v164, 0x3c000000, v1
	v_cmp_gt_f32_e32 vcc, s33, v164
	v_mul_f32_e32 v165, 0x4b800000, v164
	s_nop 0
	v_cndmask_b32_e32 v164, v164, v165, vcc
	v_rsq_f32_e32 v164, v164
	s_nop 0
	v_mul_f32_e32 v165, 0x45800000, v164
	v_cndmask_b32_e32 v164, v164, v165, vcc
	v_pk_mul_f32 v[176:177], v[100:101], v[164:165] op_sel_hi:[1,0]
	v_pk_mul_f32 v[178:179], v[102:103], v[164:165] op_sel_hi:[1,0]
	v_pk_mul_f32 v[176:177], v[136:137], v[176:177]
	v_pk_mul_f32 v[178:179], v[138:139], v[178:179]
	v_pk_mul_f32 v[180:181], v[92:93], v[164:165] op_sel_hi:[1,0]
	v_pk_mul_f32 v[164:165], v[94:95], v[164:165] op_sel_hi:[1,0]
	v_pk_mul_f32 v[180:181], v[132:133], v[180:181]
	v_pk_mul_f32 v[164:165], v[134:135], v[164:165]
	v_cvt_pk_bf16_f32 v176, v176, v177
	v_cvt_pk_bf16_f32 v177, v178, v179
	v_cvt_pk_bf16_f32 v178, v180, v181
	s_nop 0
	v_cvt_pk_bf16_f32 v179, v164, v165
	global_store_dwordx4 v[158:159], v[176:179], off
	ds_read2st64_b32 v[164:165], v172 offset0:1 offset1:5
	ds_read2st64_b32 v[176:177], v172 offset0:9 offset1:13
	v_or_b32_e32 v158, 32, v156
	v_ashrrev_i32_e32 v159, 31, v158
	s_waitcnt lgkmcnt(1)
; __device__ __forceinline__ unsigned cvtpk(float lo, float hi) { unsigned r; asm volatile("v_cvt_pk_bf16_f32 %0, %1, %2" : "=v"(r) : "v"(lo), "v"(hi)); return r; }
;     __device__ __forceinline__ void operator()(const f32x4 (&acc)[2][2][4][2], const Unit& u, int wr, int wc, int fr, int fq) const {
;     ...
; #pragma unroll
;         for (int ai = 0; ai < 2; ++ai)
; #pragma unroll
;             for (int m = 0; m < 4; ++m) { const size_t r = (size_t)(row0 + ai * HALF + m * 16);
; #pragma unroll
;                 for (int bj = 0; bj < 2; ++bj) {
;                     const int slot = ((ai * 4 + m) * 2 + bj) * 16 + fr;
;                     const float tot = (xl[(wr * 4 + 0) * 256 + slot] + xl[(wr * 4 + 1) * 256 + slot]) + (xl[(wr * 4 + 2) * 256 + slot] + xl[(wr * 4 + 3) * 256 + slot]);
;                     const float rs = rsqrtf(tot * (1.f / 128) + NORM_EPS);
;                     const f32x4 v0 = acc[ai][bj][m][0] * rs * g0, v1 = acc[ai][bj][m][1] * rs * g1;
;                     u32x4 w; w.x = cvtpk(v0[0], v0[1]); w.y = cvtpk(v0[2], v0[3]); w.z = cvtpk(v1[0], v1[1]); w.w = cvtpk(v1[2], v1[3]);
;                     *(u32x4*)(base + ((size_t)(head0 + bj) * KROWS + r) * 128) = w; } }
	v_mov_b32_e32 v178, v164
	s_waitcnt lgkmcnt(0)
	v_mov_b32_e32 v179, v176
	v_mov_b32_e32 v176, v165
	v_pk_add_f32 v[164:165], v[178:179], v[176:177]
	s_nop 0
	v_add_f32_e32 v164, v164, v165
	v_fmamk_f32 v164, v164, 0x3c000000, v1
	v_cmp_gt_f32_e32 vcc, s33, v164
	v_mul_f32_e32 v165, 0x4b800000, v164
	s_nop 0
	v_cndmask_b32_e32 v164, v164, v165, vcc
	v_rsq_f32_e32 v164, v164
	s_nop 0
	v_mul_f32_e32 v165, 0x45800000, v164
	v_cndmask_b32_e32 v164, v164, v165, vcc
	v_pk_mul_f32 v[176:177], v[104:105], v[164:165] op_sel_hi:[1,0]
	v_pk_mul_f32 v[178:179], v[106:107], v[164:165] op_sel_hi:[1,0]
	v_pk_mul_f32 v[180:181], v[96:97], v[164:165] op_sel_hi:[1,0]
	v_pk_mul_f32 v[164:165], v[98:99], v[164:165] op_sel_hi:[1,0]
	v_pk_mul_f32 v[178:179], v[138:139], v[178:179]
	v_pk_mul_f32 v[176:177], v[136:137], v[176:177]
	v_pk_mul_f32 v[164:165], v[134:135], v[164:165]
	v_pk_mul_f32 v[180:181], v[132:133], v[180:181]
	v_cvt_pk_bf16_f32 v176, v176, v177
	v_cvt_pk_bf16_f32 v177, v178, v179
	s_nop 0
	v_cvt_pk_bf16_f32 v178, v180, v181
	v_cvt_pk_bf16_f32 v179, v164, v165
	v_mad_i64_i32 v[164:165], s[62:63], s51, v203, v[158:159]
	v_lshlrev_b64 v[164:165], 8, v[164:165]
	v_lshl_add_u64 v[164:165], v[148:149], 0, v[164:165]
	global_store_dwordx4 v[164:165], v[176:179], off
	ds_read2st64_b32 v[164:165], v174 offset0:1 offset1:5
	ds_read2st64_b32 v[176:177], v174 offset0:9 offset1:13
	v_mad_i64_i32 v[158:159], s[62:63], s53, v203, v[158:159]
	v_lshlrev_b64 v[158:159], 8, v[158:159]
	s_waitcnt lgkmcnt(1)
	v_mov_b32_e32 v178, v164
	s_waitcnt lgkmcnt(0)
	v_mov_b32_e32 v179, v176
	v_mov_b32_e32 v176, v165
	v_pk_add_f32 v[164:165], v[178:179], v[176:177]
	v_lshl_add_u64 v[158:159], v[148:149], 0, v[158:159]
	v_add_f32_e32 v164, v164, v165
	v_fmamk_f32 v164, v164, 0x3c000000, v1
	v_cmp_gt_f32_e32 vcc, s33, v164
	v_mul_f32_e32 v165, 0x4b800000, v164
	s_nop 0
	v_cndmask_b32_e32 v164, v164, v165, vcc
	v_rsq_f32_e32 v164, v164
	s_nop 0
	v_mul_f32_e32 v165, 0x45800000, v164
	v_cndmask_b32_e32 v164, v164, v165, vcc
	v_pk_mul_f32 v[176:177], v[84:85], v[164:165] op_sel_hi:[1,0]
	v_pk_mul_f32 v[178:179], v[86:87], v[164:165] op_sel_hi:[1,0]
	v_pk_mul_f32 v[176:177], v[136:137], v[176:177]
	v_pk_mul_f32 v[178:179], v[138:139], v[178:179]
	v_pk_mul_f32 v[180:181], v[76:77], v[164:165] op_sel_hi:[1,0]
	v_pk_mul_f32 v[164:165], v[78:79], v[164:165] op_sel_hi:[1,0]
	v_pk_mul_f32 v[180:181], v[132:133], v[180:181]
	v_pk_mul_f32 v[164:165], v[134:135], v[164:165]
	v_cvt_pk_bf16_f32 v176, v176, v177
	v_cvt_pk_bf16_f32 v177, v178, v179
	v_cvt_pk_bf16_f32 v178, v180, v181
	s_nop 0
	v_cvt_pk_bf16_f32 v179, v164, v165
	global_store_dwordx4 v[158:159], v[176:179], off
	ds_read2st64_b32 v[164:165], v157 offset0:1 offset1:5
	ds_read2st64_b32 v[176:177], v157 offset0:9 offset1:13
	v_or_b32_e32 v158, 48, v156
	v_ashrrev_i32_e32 v159, 31, v158
	s_waitcnt lgkmcnt(1)
	v_mov_b32_e32 v178, v164
	s_waitcnt lgkmcnt(0)
	v_mov_b32_e32 v179, v176
	v_mov_b32_e32 v176, v165
	v_pk_add_f32 v[164:165], v[178:179], v[176:177]
	s_nop 0
	v_add_f32_e32 v164, v164, v165
	v_fmamk_f32 v164, v164, 0x3c000000, v1
	v_cmp_gt_f32_e32 vcc, s33, v164
	v_mul_f32_e32 v165, 0x4b800000, v164
	s_nop 0
	v_cndmask_b32_e32 v164, v164, v165, vcc
	v_rsq_f32_e32 v164, v164
	s_nop 0
	v_mul_f32_e32 v165, 0x45800000, v164
	v_cndmask_b32_e32 v164, v164, v165, vcc
	v_pk_mul_f32 v[176:177], v[88:89], v[164:165] op_sel_hi:[1,0]
	v_pk_mul_f32 v[178:179], v[90:91], v[164:165] op_sel_hi:[1,0]
	v_pk_mul_f32 v[180:181], v[80:81], v[164:165] op_sel_hi:[1,0]
	v_pk_mul_f32 v[164:165], v[82:83], v[164:165] op_sel_hi:[1,0]
	v_pk_mul_f32 v[178:179], v[138:139], v[178:179]
	v_pk_mul_f32 v[176:177], v[136:137], v[176:177]
	v_pk_mul_f32 v[164:165], v[134:135], v[164:165]
	v_pk_mul_f32 v[180:181], v[132:133], v[180:181]
	v_cvt_pk_bf16_f32 v176, v176, v177
	v_cvt_pk_bf16_f32 v177, v178, v179
	s_nop 0
	v_cvt_pk_bf16_f32 v178, v180, v181
	v_cvt_pk_bf16_f32 v179, v164, v165
	v_mad_i64_i32 v[164:165], s[62:63], s51, v203, v[158:159]
	v_lshlrev_b64 v[164:165], 8, v[164:165]
	v_lshl_add_u64 v[164:165], v[148:149], 0, v[164:165]
	global_store_dwordx4 v[164:165], v[176:179], off
	ds_read2st64_b32 v[164:165], v175 offset0:1 offset1:5
	ds_read2st64_b32 v[176:177], v175 offset0:9 offset1:13
	v_mad_i64_i32 v[158:159], s[62:63], s53, v203, v[158:159]
	v_lshlrev_b64 v[158:159], 8, v[158:159]
	s_waitcnt lgkmcnt(1)
	v_mov_b32_e32 v178, v164
	s_waitcnt lgkmcnt(0)
	v_mov_b32_e32 v179, v176
	v_mov_b32_e32 v176, v165
	v_pk_add_f32 v[164:165], v[178:179], v[176:177]
	v_lshl_add_u64 v[158:159], v[148:149], 0, v[158:159]
	v_add_f32_e32 v164, v164, v165
	v_fmamk_f32 v164, v164, 0x3c000000, v1
	v_cmp_gt_f32_e32 vcc, s33, v164
	v_mul_f32_e32 v165, 0x4b800000, v164
	s_nop 0
	v_cndmask_b32_e32 v164, v164, v165, vcc
	v_rsq_f32_e32 v164, v164
	s_nop 0
	v_mul_f32_e32 v165, 0x45800000, v164
	v_cndmask_b32_e32 v164, v164, v165, vcc
	v_pk_mul_f32 v[176:177], v[72:73], v[164:165] op_sel_hi:[1,0]
	v_pk_mul_f32 v[178:179], v[74:75], v[164:165] op_sel_hi:[1,0]
	v_pk_mul_f32 v[176:177], v[136:137], v[176:177]
	v_pk_mul_f32 v[178:179], v[138:139], v[178:179]
	v_pk_mul_f32 v[180:181], v[68:69], v[164:165] op_sel_hi:[1,0]
	v_pk_mul_f32 v[164:165], v[70:71], v[164:165] op_sel_hi:[1,0]
	v_pk_mul_f32 v[180:181], v[132:133], v[180:181]
	v_pk_mul_f32 v[164:165], v[134:135], v[164:165]
	v_cvt_pk_bf16_f32 v176, v176, v177
	v_cvt_pk_bf16_f32 v177, v178, v179
	v_cvt_pk_bf16_f32 v178, v180, v181
	s_nop 0
	v_cvt_pk_bf16_f32 v179, v164, v165
	global_store_dwordx4 v[158:159], v[176:179], off
	ds_read2st64_b32 v[164:165], v172 offset0:2 offset1:6
	ds_read2st64_b32 v[176:177], v172 offset0:10 offset1:14
	v_add_u32_e32 v158, 0x80, v156
	v_ashrrev_i32_e32 v159, 31, v158
	s_waitcnt lgkmcnt(1)
; __device__ __forceinline__ unsigned cvtpk(float lo, float hi) { unsigned r; asm volatile("v_cvt_pk_bf16_f32 %0, %1, %2" : "=v"(r) : "v"(lo), "v"(hi)); return r; }
;     __device__ __forceinline__ void operator()(const f32x4 (&acc)[2][2][4][2], const Unit& u, int wr, int wc, int fr, int fq) const {
;     ...
; #pragma unroll
;         for (int ai = 0; ai < 2; ++ai)
; #pragma unroll
;             for (int m = 0; m < 4; ++m) { const size_t r = (size_t)(row0 + ai * HALF + m * 16);
; #pragma unroll
;                 for (int bj = 0; bj < 2; ++bj) {
;                     const int slot = ((ai * 4 + m) * 2 + bj) * 16 + fr;
;                     const float tot = (xl[(wr * 4 + 0) * 256 + slot] + xl[(wr * 4 + 1) * 256 + slot]) + (xl[(wr * 4 + 2) * 256 + slot] + xl[(wr * 4 + 3) * 256 + slot]);
;                     const float rs = rsqrtf(tot * (1.f / 128) + NORM_EPS);
;                     const f32x4 v0 = acc[ai][bj][m][0] * rs * g0, v1 = acc[ai][bj][m][1] * rs * g1;
;                     u32x4 w; w.x = cvtpk(v0[0], v0[1]); w.y = cvtpk(v0[2], v0[3]); w.z = cvtpk(v1[0], v1[1]); w.w = cvtpk(v1[2], v1[3]);
;                     *(u32x4*)(base + ((size_t)(head0 + bj) * KROWS + r) * 128) = w; } }
	v_mov_b32_e32 v178, v164
	s_waitcnt lgkmcnt(0)
	v_mov_b32_e32 v179, v176
	v_mov_b32_e32 v176, v165
	v_pk_add_f32 v[164:165], v[178:179], v[176:177]
	s_nop 0
	v_add_f32_e32 v164, v164, v165
	v_fmamk_f32 v164, v164, 0x3c000000, v1
	v_cmp_gt_f32_e32 vcc, s33, v164
	v_mul_f32_e32 v165, 0x4b800000, v164
	s_nop 0
	v_cndmask_b32_e32 v164, v164, v165, vcc
	v_rsq_f32_e32 v164, v164
	s_nop 0
	v_mul_f32_e32 v165, 0x45800000, v164
	v_cndmask_b32_e32 v164, v164, v165, vcc
	v_pk_mul_f32 v[176:177], v[64:65], v[164:165] op_sel_hi:[1,0]
	v_pk_mul_f32 v[178:179], v[66:67], v[164:165] op_sel_hi:[1,0]
	v_pk_mul_f32 v[180:181], v[60:61], v[164:165] op_sel_hi:[1,0]
	v_pk_mul_f32 v[164:165], v[62:63], v[164:165] op_sel_hi:[1,0]
	v_pk_mul_f32 v[178:179], v[138:139], v[178:179]
	v_pk_mul_f32 v[176:177], v[136:137], v[176:177]
	v_pk_mul_f32 v[164:165], v[134:135], v[164:165]
	v_pk_mul_f32 v[180:181], v[132:133], v[180:181]
	v_cvt_pk_bf16_f32 v176, v176, v177
	v_cvt_pk_bf16_f32 v177, v178, v179
	s_nop 0
	v_cvt_pk_bf16_f32 v178, v180, v181
	v_cvt_pk_bf16_f32 v179, v164, v165
	v_mad_i64_i32 v[164:165], s[62:63], s51, v203, v[158:159]
	v_lshlrev_b64 v[164:165], 8, v[164:165]
	v_lshl_add_u64 v[164:165], v[148:149], 0, v[164:165]
	global_store_dwordx4 v[164:165], v[176:179], off
	ds_read2st64_b32 v[164:165], v174 offset0:2 offset1:6
	ds_read2st64_b32 v[176:177], v174 offset0:10 offset1:14
	v_mad_i64_i32 v[158:159], s[62:63], s53, v203, v[158:159]
	v_lshlrev_b64 v[158:159], 8, v[158:159]
	s_waitcnt lgkmcnt(1)
	v_mov_b32_e32 v178, v164
	s_waitcnt lgkmcnt(0)
	v_mov_b32_e32 v179, v176
	v_mov_b32_e32 v176, v165
	v_pk_add_f32 v[164:165], v[178:179], v[176:177]
	v_lshl_add_u64 v[158:159], v[148:149], 0, v[158:159]
	v_add_f32_e32 v164, v164, v165
	v_fmamk_f32 v164, v164, 0x3c000000, v1
	v_cmp_gt_f32_e32 vcc, s33, v164
	v_mul_f32_e32 v165, 0x4b800000, v164
	s_nop 0
	v_cndmask_b32_e32 v164, v164, v165, vcc
	v_rsq_f32_e32 v164, v164
	s_nop 0
	v_mul_f32_e32 v165, 0x45800000, v164
	v_cndmask_b32_e32 v164, v164, v165, vcc
	v_pk_mul_f32 v[176:177], v[52:53], v[164:165] op_sel_hi:[1,0]
	v_pk_mul_f32 v[178:179], v[54:55], v[164:165] op_sel_hi:[1,0]
	v_pk_mul_f32 v[176:177], v[136:137], v[176:177]
	v_pk_mul_f32 v[178:179], v[138:139], v[178:179]
	v_pk_mul_f32 v[180:181], v[44:45], v[164:165] op_sel_hi:[1,0]
	v_pk_mul_f32 v[164:165], v[46:47], v[164:165] op_sel_hi:[1,0]
	v_pk_mul_f32 v[180:181], v[132:133], v[180:181]
	v_pk_mul_f32 v[164:165], v[134:135], v[164:165]
	v_cvt_pk_bf16_f32 v176, v176, v177
	v_cvt_pk_bf16_f32 v177, v178, v179
	v_cvt_pk_bf16_f32 v178, v180, v181
	s_nop 0
	v_cvt_pk_bf16_f32 v179, v164, v165
	global_store_dwordx4 v[158:159], v[176:179], off
	ds_read2st64_b32 v[164:165], v157 offset0:2 offset1:6
	ds_read2st64_b32 v[176:177], v157 offset0:10 offset1:14
	v_add_u32_e32 v158, 0x90, v156
	v_ashrrev_i32_e32 v159, 31, v158
	s_waitcnt lgkmcnt(1)
	v_mov_b32_e32 v178, v164
	s_waitcnt lgkmcnt(0)
	v_mov_b32_e32 v179, v176
	v_mov_b32_e32 v176, v165
	v_pk_add_f32 v[164:165], v[178:179], v[176:177]
	s_nop 0
	v_add_f32_e32 v164, v164, v165
	v_fmamk_f32 v164, v164, 0x3c000000, v1
	v_cmp_gt_f32_e32 vcc, s33, v164
	v_mul_f32_e32 v165, 0x4b800000, v164
	s_nop 0
	v_cndmask_b32_e32 v164, v164, v165, vcc
	v_rsq_f32_e32 v164, v164
	s_nop 0
	v_mul_f32_e32 v165, 0x45800000, v164
	v_cndmask_b32_e32 v164, v164, v165, vcc
	v_pk_mul_f32 v[176:177], v[56:57], v[164:165] op_sel_hi:[1,0]
	v_pk_mul_f32 v[178:179], v[58:59], v[164:165] op_sel_hi:[1,0]
	v_pk_mul_f32 v[180:181], v[48:49], v[164:165] op_sel_hi:[1,0]
	v_pk_mul_f32 v[164:165], v[50:51], v[164:165] op_sel_hi:[1,0]
	v_pk_mul_f32 v[178:179], v[138:139], v[178:179]
	v_pk_mul_f32 v[176:177], v[136:137], v[176:177]
	v_pk_mul_f32 v[164:165], v[134:135], v[164:165]
	v_pk_mul_f32 v[180:181], v[132:133], v[180:181]
	v_cvt_pk_bf16_f32 v176, v176, v177
	v_cvt_pk_bf16_f32 v177, v178, v179
	s_nop 0
	v_cvt_pk_bf16_f32 v178, v180, v181
	v_cvt_pk_bf16_f32 v179, v164, v165
	v_mad_i64_i32 v[164:165], s[62:63], s51, v203, v[158:159]
	v_lshlrev_b64 v[164:165], 8, v[164:165]
	v_lshl_add_u64 v[164:165], v[148:149], 0, v[164:165]
	global_store_dwordx4 v[164:165], v[176:179], off
	ds_read2st64_b32 v[164:165], v175 offset0:2 offset1:6
	ds_read2st64_b32 v[176:177], v175 offset0:10 offset1:14
	v_mad_i64_i32 v[158:159], s[62:63], s53, v203, v[158:159]
	v_lshlrev_b64 v[158:159], 8, v[158:159]
	s_waitcnt lgkmcnt(1)
	v_mov_b32_e32 v178, v164
	s_waitcnt lgkmcnt(0)
	v_mov_b32_e32 v179, v176
	v_mov_b32_e32 v176, v165
	v_pk_add_f32 v[164:165], v[178:179], v[176:177]
	v_lshl_add_u64 v[158:159], v[148:149], 0, v[158:159]
	v_add_f32_e32 v164, v164, v165
	v_fmamk_f32 v164, v164, 0x3c000000, v1
	v_cmp_gt_f32_e32 vcc, s33, v164
	v_mul_f32_e32 v165, 0x4b800000, v164
	s_nop 0
	v_cndmask_b32_e32 v164, v164, v165, vcc
	v_rsq_f32_e32 v164, v164
	s_nop 0
	v_mul_f32_e32 v165, 0x45800000, v164
	v_cndmask_b32_e32 v164, v164, v165, vcc
	v_pk_mul_f32 v[176:177], v[36:37], v[164:165] op_sel_hi:[1,0]
	v_pk_mul_f32 v[178:179], v[38:39], v[164:165] op_sel_hi:[1,0]
	v_pk_mul_f32 v[176:177], v[136:137], v[176:177]
	v_pk_mul_f32 v[178:179], v[138:139], v[178:179]
	v_pk_mul_f32 v[180:181], v[28:29], v[164:165] op_sel_hi:[1,0]
	v_pk_mul_f32 v[164:165], v[30:31], v[164:165] op_sel_hi:[1,0]
	v_pk_mul_f32 v[180:181], v[132:133], v[180:181]
	v_pk_mul_f32 v[164:165], v[134:135], v[164:165]
	v_cvt_pk_bf16_f32 v176, v176, v177
	v_cvt_pk_bf16_f32 v177, v178, v179
	v_cvt_pk_bf16_f32 v178, v180, v181
	s_nop 0
	v_cvt_pk_bf16_f32 v179, v164, v165
	global_store_dwordx4 v[158:159], v[176:179], off
	ds_read2st64_b32 v[164:165], v172 offset0:3 offset1:7
	ds_read2st64_b32 v[176:177], v172 offset0:11 offset1:15
	v_add_u32_e32 v158, 0xa0, v156
	v_ashrrev_i32_e32 v159, 31, v158
	s_waitcnt lgkmcnt(1)
; __device__ __forceinline__ unsigned cvtpk(float lo, float hi) { unsigned r; asm volatile("v_cvt_pk_bf16_f32 %0, %1, %2" : "=v"(r) : "v"(lo), "v"(hi)); return r; }
;     __device__ __forceinline__ void operator()(const f32x4 (&acc)[2][2][4][2], const Unit& u, int wr, int wc, int fr, int fq) const {
;     ...
; #pragma unroll
;         for (int ai = 0; ai < 2; ++ai)
; #pragma unroll
;             for (int m = 0; m < 4; ++m) { const size_t r = (size_t)(row0 + ai * HALF + m * 16);
; #pragma unroll
;                 for (int bj = 0; bj < 2; ++bj) {
;                     const int slot = ((ai * 4 + m) * 2 + bj) * 16 + fr;
;                     const float tot = (xl[(wr * 4 + 0) * 256 + slot] + xl[(wr * 4 + 1) * 256 + slot]) + (xl[(wr * 4 + 2) * 256 + slot] + xl[(wr * 4 + 3) * 256 + slot]);
;                     const float rs = rsqrtf(tot * (1.f / 128) + NORM_EPS);
;                     const f32x4 v0 = acc[ai][bj][m][0] * rs * g0, v1 = acc[ai][bj][m][1] * rs * g1;
;                     u32x4 w; w.x = cvtpk(v0[0], v0[1]); w.y = cvtpk(v0[2], v0[3]); w.z = cvtpk(v1[0], v1[1]); w.w = cvtpk(v1[2], v1[3]);
;                     *(u32x4*)(base + ((size_t)(head0 + bj) * KROWS + r) * 128) = w; } }
	v_mov_b32_e32 v178, v164
	s_waitcnt lgkmcnt(0)
	v_mov_b32_e32 v179, v176
	v_mov_b32_e32 v176, v165
	v_pk_add_f32 v[164:165], v[178:179], v[176:177]
	s_nop 0
	v_add_f32_e32 v164, v164, v165
	v_fmamk_f32 v164, v164, 0x3c000000, v1
	v_cmp_gt_f32_e32 vcc, s33, v164
	v_mul_f32_e32 v165, 0x4b800000, v164
	s_nop 0
	v_cndmask_b32_e32 v164, v164, v165, vcc
	v_rsq_f32_e32 v164, v164
	s_nop 0
	v_mul_f32_e32 v165, 0x45800000, v164
	v_cndmask_b32_e32 v164, v164, v165, vcc
	v_pk_mul_f32 v[176:177], v[40:41], v[164:165] op_sel_hi:[1,0]
	v_pk_mul_f32 v[178:179], v[42:43], v[164:165] op_sel_hi:[1,0]
	v_pk_mul_f32 v[180:181], v[32:33], v[164:165] op_sel_hi:[1,0]
	v_pk_mul_f32 v[164:165], v[34:35], v[164:165] op_sel_hi:[1,0]
	v_pk_mul_f32 v[178:179], v[138:139], v[178:179]
	v_pk_mul_f32 v[176:177], v[136:137], v[176:177]
	v_pk_mul_f32 v[164:165], v[134:135], v[164:165]
	v_pk_mul_f32 v[180:181], v[132:133], v[180:181]
	v_cvt_pk_bf16_f32 v176, v176, v177
	v_cvt_pk_bf16_f32 v177, v178, v179
	s_nop 0
	v_cvt_pk_bf16_f32 v178, v180, v181
	v_cvt_pk_bf16_f32 v179, v164, v165
	v_mad_i64_i32 v[164:165], s[62:63], s51, v203, v[158:159]
	v_lshlrev_b64 v[164:165], 8, v[164:165]
	v_lshl_add_u64 v[164:165], v[148:149], 0, v[164:165]
	global_store_dwordx4 v[164:165], v[176:179], off
	ds_read2st64_b32 v[164:165], v174 offset0:3 offset1:7
	ds_read2st64_b32 v[176:177], v174 offset0:11 offset1:15
	v_mad_i64_i32 v[158:159], s[62:63], s53, v203, v[158:159]
	v_lshlrev_b64 v[158:159], 8, v[158:159]
	s_waitcnt lgkmcnt(1)
	v_mov_b32_e32 v178, v164
	s_waitcnt lgkmcnt(0)
	v_mov_b32_e32 v179, v176
	v_mov_b32_e32 v176, v165
	v_pk_add_f32 v[164:165], v[178:179], v[176:177]
	v_lshl_add_u64 v[158:159], v[148:149], 0, v[158:159]
	v_add_f32_e32 v164, v164, v165
	v_fmamk_f32 v164, v164, 0x3c000000, v1
	v_cmp_gt_f32_e32 vcc, s33, v164
	v_mul_f32_e32 v165, 0x4b800000, v164
	s_nop 0
	v_cndmask_b32_e32 v164, v164, v165, vcc
	v_rsq_f32_e32 v164, v164
	s_nop 0
	v_mul_f32_e32 v165, 0x45800000, v164
	v_cndmask_b32_e32 v164, v164, v165, vcc
	v_pk_mul_f32 v[176:177], v[20:21], v[164:165] op_sel_hi:[1,0]
	v_pk_mul_f32 v[178:179], v[22:23], v[164:165] op_sel_hi:[1,0]
	v_pk_mul_f32 v[176:177], v[136:137], v[176:177]
	v_pk_mul_f32 v[178:179], v[138:139], v[178:179]
	v_pk_mul_f32 v[180:181], v[12:13], v[164:165] op_sel_hi:[1,0]
	v_pk_mul_f32 v[164:165], v[14:15], v[164:165] op_sel_hi:[1,0]
	v_pk_mul_f32 v[180:181], v[132:133], v[180:181]
	v_pk_mul_f32 v[164:165], v[134:135], v[164:165]
	v_cvt_pk_bf16_f32 v176, v176, v177
	v_cvt_pk_bf16_f32 v177, v178, v179
	v_cvt_pk_bf16_f32 v178, v180, v181
	s_nop 0
	v_cvt_pk_bf16_f32 v179, v164, v165
	global_store_dwordx4 v[158:159], v[176:179], off
	ds_read2st64_b32 v[164:165], v157 offset0:3 offset1:7
	ds_read2st64_b32 v[176:177], v157 offset0:11 offset1:15
	v_add_u32_e32 v158, 0xb0, v156
	v_ashrrev_i32_e32 v159, 31, v158
	s_waitcnt lgkmcnt(1)
	v_mov_b32_e32 v178, v164
	s_waitcnt lgkmcnt(0)
	v_mov_b32_e32 v179, v176
	v_mov_b32_e32 v176, v165
	v_pk_add_f32 v[164:165], v[178:179], v[176:177]
	s_nop 0
	v_add_f32_e32 v157, v164, v165
	v_fmamk_f32 v157, v157, 0x3c000000, v1
	v_cmp_gt_f32_e32 vcc, s33, v157
	v_mul_f32_e32 v164, 0x4b800000, v157
	s_nop 0
	v_cndmask_b32_e32 v157, v157, v164, vcc
	v_rsq_f32_e32 v157, v157
	s_nop 0
	v_mul_f32_e32 v164, 0x45800000, v157
	v_cndmask_b32_e32 v164, v157, v164, vcc
	v_pk_mul_f32 v[176:177], v[24:25], v[164:165] op_sel_hi:[1,0]
	v_pk_mul_f32 v[178:179], v[26:27], v[164:165] op_sel_hi:[1,0]
	v_pk_mul_f32 v[180:181], v[16:17], v[164:165] op_sel_hi:[1,0]
	v_pk_mul_f32 v[164:165], v[18:19], v[164:165] op_sel_hi:[1,0]
	v_pk_mul_f32 v[178:179], v[138:139], v[178:179]
	v_pk_mul_f32 v[176:177], v[136:137], v[176:177]
	v_pk_mul_f32 v[164:165], v[134:135], v[164:165]
	v_pk_mul_f32 v[180:181], v[132:133], v[180:181]
	v_cvt_pk_bf16_f32 v176, v176, v177
	v_cvt_pk_bf16_f32 v177, v178, v179
	s_nop 0
	v_cvt_pk_bf16_f32 v178, v180, v181
	v_cvt_pk_bf16_f32 v179, v164, v165
	v_mad_i64_i32 v[164:165], s[62:63], s51, v203, v[158:159]
	v_lshlrev_b64 v[164:165], 8, v[164:165]
	v_lshl_add_u64 v[164:165], v[148:149], 0, v[164:165]
	global_store_dwordx4 v[164:165], v[176:179], off
	ds_read2st64_b32 v[164:165], v175 offset0:3 offset1:7
	ds_read2st64_b32 v[174:175], v175 offset0:11 offset1:15
	s_waitcnt lgkmcnt(1)
	v_mov_b32_e32 v176, v164
	s_waitcnt lgkmcnt(0)
	v_mov_b32_e32 v177, v174
	v_mov_b32_e32 v174, v165
	v_pk_add_f32 v[164:165], v[176:177], v[174:175]
	s_nop 0
	v_add_f32_e32 v157, v164, v165
	v_fmamk_f32 v157, v157, 0x3c000000, v1
	v_cmp_gt_f32_e32 vcc, s33, v157
	v_mul_f32_e32 v164, 0x4b800000, v157
	s_nop 0
	v_cndmask_b32_e32 v157, v157, v164, vcc
	v_rsq_f32_e32 v157, v157
	s_nop 0
	v_mul_f32_e32 v164, 0x45800000, v157
	v_cndmask_b32_e32 v164, v157, v164, vcc
	v_pk_mul_f32 v[174:175], v[8:9], v[164:165] op_sel_hi:[1,0]
	v_pk_mul_f32 v[176:177], v[10:11], v[164:165] op_sel_hi:[1,0]
	v_pk_mul_f32 v[136:137], v[136:137], v[174:175]
	v_pk_mul_f32 v[174:175], v[4:5], v[164:165] op_sel_hi:[1,0]
	v_pk_mul_f32 v[164:165], v[6:7], v[164:165] op_sel_hi:[1,0]
	v_pk_mul_f32 v[138:139], v[138:139], v[176:177]
	v_pk_mul_f32 v[164:165], v[134:135], v[164:165]
	v_pk_mul_f32 v[134:135], v[132:133], v[174:175]
	v_cvt_pk_bf16_f32 v132, v136, v137
	v_mad_i64_i32 v[136:137], s[62:63], s53, v203, v[158:159]
	v_cvt_pk_bf16_f32 v133, v138, v139
	v_cvt_pk_bf16_f32 v134, v134, v135
	v_cvt_pk_bf16_f32 v135, v164, v165
	v_mov_b64_e32 v[138:139], v[148:149]
	s_branch .LBB0_774

; #define PG8_STAGE(bufoff, gbase, voff) do { _Pragma("unroll") for (int _i = 0; _i < 2; ++_i) \
;         __builtin_amdgcn_global_load_lds((const unsigned*)((const char*)(gbase) + (voff)[_i]), (PG8_LAS unsigned*)(lds + (bufoff) + ldsw + _i * 8192), 16, 0, 0); } while (0)
; #define PG8_WAIT_V(n) asm volatile("s_waitcnt vmcnt(" #n ")" ::: "memory")
; #define PG8_BAR __builtin_amdgcn_s_barrier()
;     __device__ __forceinline__ void operator()(const f32x4 (&acc)[2][2][4][2], const Unit& u, int wr, int wc, int fr, int fq) const {
;     ...
;         const int colh = wc * 32 + 8 * fq;
;         const f32x4 g0 = *(const f32x4*)(g + colh), g1 = *(const f32x4*)(g + colh + 4);
;         const int head0 = colt >> 7;
;         bf16_t* base = Kn + colh;
; template <class Epi, class Sched, bool ALIGN_EPI = false, bool SP2 = false>
; __device__ __forceinline__ void gemm_phase(PG8_LAS unsigned char* lds, const Gemm g, const Sched& S, const Epi& E) {
;     ...
;         PG8_STAGE(PG8_SB(1, 0), cB + kstep, voffB); PG8_STAGE(PG8_SA(1, 0), cA + kstep, voffA); PG8_STAGE(PG8_SB(1, 1), cB + hstep + kstep, voffB);
;         PG8_WAIT_V(6); PG8_BAR;
.LBB0_788:
	s_and_b32 s43, s40, 3
	s_add_i32 m0, s60, 0x18000
	v_lshl_add_u64 v[10:11], v[10:11], 0, s[28:29]
	s_lshl_b32 s46, s42, 13
	s_lshl_b32 s47, s43, 12
	s_waitcnt vmcnt(2)
	s_barrier
	global_load_lds_dwordx4 v[10:11], off
	v_lshl_add_u64 v[8:9], v[8:9], 0, s[28:29]
	s_add_i32 m0, s60, 0x1a000
	s_add_i32 s64, s60, 0x8000
	s_add_i32 s65, s60, 0xa000
	global_load_lds_dwordx4 v[8:9], off
	v_lshl_add_u64 v[4:5], v[4:5], 0, s[28:29]
	s_mov_b32 m0, s64
	s_add_u32 s40, s54, 0x20080
	global_load_lds_dwordx4 v[4:5], off
	v_lshl_add_u64 v[4:5], v[6:7], 0, s[28:29]
	s_mov_b32 m0, s65
	s_addc_u32 s41, s55, 0
	global_load_lds_dwordx4 v[4:5], off
	s_add_i32 m0, s60, 0x1c000
	v_lshl_add_u64 v[4:5], s[40:41], 0, v[2:3]
	global_load_lds_dwordx4 v[4:5], off
	v_lshl_add_u64 v[4:5], s[40:41], 0, v[140:141]
	s_add_i32 m0, s60, 0x1e000
	v_bfe_u32 v6, v12, 4, 2
	global_load_lds_dwordx4 v[4:5], off
	v_and_b32_e32 v5, 15, v12
	v_lshlrev_b32_e32 v4, 4, v6
	v_lshl_or_b32 v161, s42, 6, v5
	v_lshl_or_b32 v8, v5, 6, v4
	v_lshlrev_b32_e32 v5, 2, v5
	v_lshlrev_b32_e32 v7, 3, v6
	v_and_b32_e32 v9, 32, v5
	s_cmpk_lt_u32 s3, 0x100
	v_bitop3_b32 v10, v8, s46, v9 bitop3:0xde
	v_bitop3_b32 v162, v8, s47, v9 bitop3:0xde
	s_cselect_b64 s[40:41], -1, 0
	s_lshl_b32 s42, s42, 12
	v_lshl_or_b32 v8, s43, 5, v7
	s_sext_i32_i8 s68, s2
	v_cmp_eq_u32_e64 s[2:3], 0, v6
	s_add_i32 s42, s42, 0
	v_lshlrev_b32_e32 v6, 2, v8
	v_mov_b32_e32 v7, v3
	s_lshl_b32 s46, s43, 10
	s_add_i32 s42, s42, 0x20400
	v_lshl_add_u64 v[146:147], s[36:37], 0, v[6:7]
	global_load_dwordx4 v[20:23], v[146:147], off offset:16
	global_load_dwordx4 v[24:27], v[146:147], off
	v_add_u32_e32 v146, 0x23500, v6
	s_waitcnt vmcnt(0)
	ds_write_b128 v146, v[20:23] offset:16
	ds_write_b128 v146, v[24:27]
	s_waitcnt lgkmcnt(0)
	v_lshlrev_b32_e32 v6, 1, v8
	s_ashr_i32 s67, s73, 31
	s_add_i32 s46, s42, s46
	v_lshl_add_u64 v[148:149], s[4:5], 0, v[6:7]
	s_lshl_b32 s4, s43, 6
	s_add_u32 s4, s19, s4
	v_add_u32_e32 v163, s46, v5
	v_add_u32_e32 v172, s42, v5
	s_addc_u32 s5, s79, 0
	v_mov_b32_e32 v5, v3
	v_lshl_add_u64 v[150:151], s[4:5], 0, v[4:5]
	v_lshlrev_b32_e32 v4, 13, v17
	v_and_b32_e32 v4, 0xffffc000, v4
	v_lshl_add_u32 v4, v16, 10, v4
	v_and_b32_e32 v5, 1, v17
	v_lshl_or_b32 v4, v5, 6, v4
	v_lshl_add_u32 v152, v18, 1, v4
	v_lshlrev_b32_e32 v4, 13, v13
	v_and_b32_e32 v4, 0xffffc000, v4
	s_waitcnt vmcnt(6)
	v_lshl_add_u32 v4, v14, 10, v4
	v_and_b32_e32 v5, 1, v13
	v_lshl_or_b32 v4, v5, 6, v4
	s_mov_b32 s66, 0
	v_mov_b32_e32 v153, v3
	v_lshl_add_u32 v154, v15, 1, v4
	v_mov_b32_e32 v155, v3
	v_add_u32_e32 v173, 0, v10
	s_barrier
	s_branch .LBB0_791

; __device__ __forceinline__ unsigned cvtpk(float lo, float hi) { unsigned r; asm volatile("v_cvt_pk_bf16_f32 %0, %1, %2" : "=v"(r) : "v"(lo), "v"(hi)); return r; }
;     __device__ __forceinline__ void operator()(const f32x4 (&acc)[2][2][4][2], const Unit& u, int wr, int wc, int fr, int fq) const {
;     ...
;         asm volatile("s_waitcnt lgkmcnt(0)" ::: "memory"); __builtin_amdgcn_s_barrier(); asm volatile("" ::: "memory");
;         const int colh = wc * 32 + 8 * fq;
;         const f32x4 g0 = *(const f32x4*)(g + colh), g1 = *(const f32x4*)(g + colh + 4);
;         const int head0 = colt >> 7;
;         bf16_t* base = Kn + colh;
; #pragma unroll
;         for (int ai = 0; ai < 2; ++ai)
; #pragma unroll
;             for (int m = 0; m < 4; ++m) { const size_t r = (size_t)(row0 + ai * HALF + m * 16);
; #pragma unroll
;                 for (int bj = 0; bj < 2; ++bj) {
;                     const int slot = ((ai * 4 + m) * 2 + bj) * 16 + fr;
;                     const float tot = (xl[(wr * 4 + 0) * 256 + slot] + xl[(wr * 4 + 1) * 256 + slot]) + (xl[(wr * 4 + 2) * 256 + slot] + xl[(wr * 4 + 3) * 256 + slot]);
;                     const float rs = rsqrtf(tot * (1.f / 128) + NORM_EPS);
;                     const f32x4 v0 = acc[ai][bj][m][0] * rs * g0, v1 = acc[ai][bj][m][1] * rs * g1;
;                     u32x4 w; w.x = cvtpk(v0[0], v0[1]); w.y = cvtpk(v0[2], v0[3]); w.z = cvtpk(v1[0], v1[1]); w.w = cvtpk(v1[2], v1[3]);
;                     *(u32x4*)(base + ((size_t)(head0 + bj) * KROWS + r) * 128) = w; } }
.LBB0_800:
	s_or_b64 exec, exec, s[50:51]
	s_waitcnt lgkmcnt(0)
	s_barrier
	s_waitcnt lgkmcnt(0)
	ds_read_b128 v[132:135], v146 offset:16
	ds_read_b128 v[136:139], v146
	ds_read2st64_b32 v[158:159], v172 offset1:4
	ds_read2st64_b32 v[164:165], v172 offset0:8 offset1:12
	s_lshl_b32 s19, s68, 1
	v_ashrrev_i32_e32 v157, 31, v156
	s_or_b32 s37, s19, 1
	s_waitcnt lgkmcnt(0)
	v_mov_b32_e32 v174, v158
	v_mov_b32_e32 v175, v164
	v_mov_b32_e32 v164, v159
	v_pk_add_f32 v[158:159], v[174:175], v[164:165]
	s_nop 0
	v_add_f32_e32 v158, v158, v159
	v_fmamk_f32 v158, v158, 0x3c000000, v1
	v_cmp_gt_f32_e32 vcc, s33, v158
	v_mul_f32_e32 v159, 0x4b800000, v158
	s_nop 0
	v_cndmask_b32_e32 v158, v158, v159, vcc
	v_rsq_f32_e32 v158, v158
	s_nop 0
	v_mul_f32_e32 v159, 0x45800000, v158
	v_cndmask_b32_e32 v158, v158, v159, vcc
	v_pk_mul_f32 v[174:175], v[130:131], v[158:159] op_sel_hi:[1,0]
	v_pk_mul_f32 v[164:165], v[128:129], v[158:159] op_sel_hi:[1,0]
	v_pk_mul_f32 v[176:177], v[138:139], v[174:175]
	v_pk_mul_f32 v[174:175], v[124:125], v[158:159] op_sel_hi:[1,0]
	v_pk_mul_f32 v[158:159], v[126:127], v[158:159] op_sel_hi:[1,0]
	v_pk_mul_f32 v[164:165], v[136:137], v[164:165]
	v_pk_mul_f32 v[158:159], v[134:135], v[158:159]
	v_pk_mul_f32 v[178:179], v[132:133], v[174:175]
	v_cvt_pk_bf16_f32 v174, v164, v165
	v_cvt_pk_bf16_f32 v175, v176, v177
	s_nop 0
	v_cvt_pk_bf16_f32 v176, v178, v179
	v_cvt_pk_bf16_f32 v177, v158, v159
	v_mad_i64_i32 v[158:159], s[50:51], s19, v203, v[156:157]
	v_lshlrev_b64 v[158:159], 8, v[158:159]
	v_lshl_add_u64 v[158:159], v[148:149], 0, v[158:159]
	global_store_dwordx4 v[158:159], v[174:177], off
	s_nop 1
	v_add_u32_e32 v174, 64, v172
	ds_read2st64_b32 v[158:159], v174 offset1:4
	ds_read2st64_b32 v[164:165], v174 offset0:8 offset1:12
	v_add_u32_e32 v175, 0xc0, v172
	s_waitcnt lgkmcnt(1)
	v_mov_b32_e32 v176, v158
	s_waitcnt lgkmcnt(0)
	v_mov_b32_e32 v177, v164
	v_mov_b32_e32 v164, v159
	v_pk_add_f32 v[158:159], v[176:177], v[164:165]
	s_nop 0
	v_add_f32_e32 v158, v158, v159
	v_fmamk_f32 v158, v158, 0x3c000000, v1
	v_cmp_gt_f32_e32 vcc, s33, v158
	v_mul_f32_e32 v159, 0x4b800000, v158
	s_nop 0
	v_cndmask_b32_e32 v158, v158, v159, vcc
	v_rsq_f32_e32 v158, v158
	s_nop 0
	v_mul_f32_e32 v159, 0x45800000, v158
	v_cndmask_b32_e32 v158, v158, v159, vcc
	v_pk_mul_f32 v[176:177], v[122:123], v[158:159] op_sel_hi:[1,0]
	v_pk_mul_f32 v[164:165], v[120:121], v[158:159] op_sel_hi:[1,0]
	v_pk_mul_f32 v[178:179], v[138:139], v[176:177]
	v_pk_mul_f32 v[176:177], v[112:113], v[158:159] op_sel_hi:[1,0]
	v_pk_mul_f32 v[158:159], v[114:115], v[158:159] op_sel_hi:[1,0]
	v_pk_mul_f32 v[164:165], v[136:137], v[164:165]
	v_pk_mul_f32 v[158:159], v[134:135], v[158:159]
	v_pk_mul_f32 v[180:181], v[132:133], v[176:177]
	v_cvt_pk_bf16_f32 v176, v164, v165
	v_cvt_pk_bf16_f32 v177, v178, v179
	s_nop 0
	v_cvt_pk_bf16_f32 v178, v180, v181
	v_cvt_pk_bf16_f32 v179, v158, v159
	v_mad_i64_i32 v[158:159], s[50:51], s37, v203, v[156:157]
	v_lshlrev_b64 v[158:159], 8, v[158:159]
	v_lshl_add_u64 v[158:159], v[148:149], 0, v[158:159]
	global_store_dwordx4 v[158:159], v[176:179], off
	v_add_u32_e32 v157, 0x80, v172
	ds_read2st64_b32 v[164:165], v157 offset1:4
	ds_read2st64_b32 v[176:177], v157 offset0:8 offset1:12
	v_or_b32_e32 v158, 16, v156
	v_ashrrev_i32_e32 v159, 31, v158
	s_waitcnt lgkmcnt(1)
	v_mov_b32_e32 v178, v164
	s_waitcnt lgkmcnt(0)
	v_mov_b32_e32 v179, v176
	v_mov_b32_e32 v176, v165
	v_pk_add_f32 v[164:165], v[178:179], v[176:177]
	s_nop 0
	v_add_f32_e32 v164, v164, v165
	v_fmamk_f32 v164, v164, 0x3c000000, v1
	v_cmp_gt_f32_e32 vcc, s33, v164
	v_mul_f32_e32 v165, 0x4b800000, v164
	s_nop 0
	v_cndmask_b32_e32 v164, v164, v165, vcc
	v_rsq_f32_e32 v164, v164
	s_nop 0
	v_mul_f32_e32 v165, 0x45800000, v164
	v_cndmask_b32_e32 v164, v164, v165, vcc
	v_pk_mul_f32 v[176:177], v[116:117], v[164:165] op_sel_hi:[1,0]
	v_pk_mul_f32 v[178:179], v[118:119], v[164:165] op_sel_hi:[1,0]
	v_pk_mul_f32 v[180:181], v[108:109], v[164:165] op_sel_hi:[1,0]
	v_pk_mul_f32 v[164:165], v[110:111], v[164:165] op_sel_hi:[1,0]
	v_pk_mul_f32 v[178:179], v[138:139], v[178:179]
	v_pk_mul_f32 v[176:177], v[136:137], v[176:177]
	v_pk_mul_f32 v[164:165], v[134:135], v[164:165]
	v_pk_mul_f32 v[180:181], v[132:133], v[180:181]
	v_cvt_pk_bf16_f32 v176, v176, v177
	v_cvt_pk_bf16_f32 v177, v178, v179
	s_nop 0
	v_cvt_pk_bf16_f32 v178, v180, v181
	v_cvt_pk_bf16_f32 v179, v164, v165
	v_mad_i64_i32 v[164:165], s[50:51], s19, v203, v[158:159]
	v_lshlrev_b64 v[164:165], 8, v[164:165]
	v_lshl_add_u64 v[164:165], v[148:149], 0, v[164:165]
	global_store_dwordx4 v[164:165], v[176:179], off
	ds_read2st64_b32 v[164:165], v175 offset1:4
	ds_read2st64_b32 v[176:177], v175 offset0:8 offset1:12
	v_mad_i64_i32 v[158:159], s[50:51], s37, v203, v[158:159]
	v_lshlrev_b64 v[158:159], 8, v[158:159]
	s_waitcnt lgkmcnt(1)
	v_mov_b32_e32 v178, v164
	s_waitcnt lgkmcnt(0)
	v_mov_b32_e32 v179, v176
	v_mov_b32_e32 v176, v165
	v_pk_add_f32 v[164:165], v[178:179], v[176:177]
	v_lshl_add_u64 v[158:159], v[148:149], 0, v[158:159]
	v_add_f32_e32 v164, v164, v165
	v_fmamk_f32 v164, v164, 0x3c000000, v1
	v_cmp_gt_f32_e32 vcc, s33, v164
	v_mul_f32_e32 v165, 0x4b800000, v164
	s_nop 0
	v_cndmask_b32_e32 v164, v164, v165, vcc
	v_rsq_f32_e32 v164, v164
	s_nop 0
	v_mul_f32_e32 v165, 0x45800000, v164
	v_cndmask_b32_e32 v164, v164, v165, vcc
	v_pk_mul_f32 v[176:177], v[100:101], v[164:165] op_sel_hi:[1,0]
	v_pk_mul_f32 v[178:179], v[102:103], v[164:165] op_sel_hi:[1,0]
	v_pk_mul_f32 v[176:177], v[136:137], v[176:177]
	v_pk_mul_f32 v[178:179], v[138:139], v[178:179]
	v_pk_mul_f32 v[180:181], v[92:93], v[164:165] op_sel_hi:[1,0]
	v_pk_mul_f32 v[164:165], v[94:95], v[164:165] op_sel_hi:[1,0]
	v_pk_mul_f32 v[180:181], v[132:133], v[180:181]
	v_pk_mul_f32 v[164:165], v[134:135], v[164:165]
	v_cvt_pk_bf16_f32 v176, v176, v177
	v_cvt_pk_bf16_f32 v177, v178, v179
	v_cvt_pk_bf16_f32 v178, v180, v181
	s_nop 0
	v_cvt_pk_bf16_f32 v179, v164, v165
	global_store_dwordx4 v[158:159], v[176:179], off
	ds_read2st64_b32 v[164:165], v172 offset0:1 offset1:5
	ds_read2st64_b32 v[176:177], v172 offset0:9 offset1:13
	v_or_b32_e32 v158, 32, v156
	v_ashrrev_i32_e32 v159, 31, v158
	s_waitcnt lgkmcnt(1)
; __device__ __forceinline__ unsigned cvtpk(float lo, float hi) { unsigned r; asm volatile("v_cvt_pk_bf16_f32 %0, %1, %2" : "=v"(r) : "v"(lo), "v"(hi)); return r; }
;     __device__ __forceinline__ void operator()(const f32x4 (&acc)[2][2][4][2], const Unit& u, int wr, int wc, int fr, int fq) const {
;     ...
; #pragma unroll
;         for (int ai = 0; ai < 2; ++ai)
; #pragma unroll
;             for (int m = 0; m < 4; ++m) { const size_t r = (size_t)(row0 + ai * HALF + m * 16);
; #pragma unroll
;                 for (int bj = 0; bj < 2; ++bj) {
;                     const int slot = ((ai * 4 + m) * 2 + bj) * 16 + fr;
;                     const float tot = (xl[(wr * 4 + 0) * 256 + slot] + xl[(wr * 4 + 1) * 256 + slot]) + (xl[(wr * 4 + 2) * 256 + slot] + xl[(wr * 4 + 3) * 256 + slot]);
;                     const float rs = rsqrtf(tot * (1.f / 128) + NORM_EPS);
;                     const f32x4 v0 = acc[ai][bj][m][0] * rs * g0, v1 = acc[ai][bj][m][1] * rs * g1;
;                     u32x4 w; w.x = cvtpk(v0[0], v0[1]); w.y = cvtpk(v0[2], v0[3]); w.z = cvtpk(v1[0], v1[1]); w.w = cvtpk(v1[2], v1[3]);
;                     *(u32x4*)(base + ((size_t)(head0 + bj) * KROWS + r) * 128) = w; } }
	v_mov_b32_e32 v178, v164
	s_waitcnt lgkmcnt(0)
	v_mov_b32_e32 v179, v176
	v_mov_b32_e32 v176, v165
	v_pk_add_f32 v[164:165], v[178:179], v[176:177]
	s_nop 0
	v_add_f32_e32 v164, v164, v165
	v_fmamk_f32 v164, v164, 0x3c000000, v1
	v_cmp_gt_f32_e32 vcc, s33, v164
	v_mul_f32_e32 v165, 0x4b800000, v164
	s_nop 0
	v_cndmask_b32_e32 v164, v164, v165, vcc
	v_rsq_f32_e32 v164, v164
	s_nop 0
	v_mul_f32_e32 v165, 0x45800000, v164
	v_cndmask_b32_e32 v164, v164, v165, vcc
	v_pk_mul_f32 v[176:177], v[104:105], v[164:165] op_sel_hi:[1,0]
	v_pk_mul_f32 v[178:179], v[106:107], v[164:165] op_sel_hi:[1,0]
	v_pk_mul_f32 v[180:181], v[96:97], v[164:165] op_sel_hi:[1,0]
	v_pk_mul_f32 v[164:165], v[98:99], v[164:165] op_sel_hi:[1,0]
	v_pk_mul_f32 v[178:179], v[138:139], v[178:179]
	v_pk_mul_f32 v[176:177], v[136:137], v[176:177]
	v_pk_mul_f32 v[164:165], v[134:135], v[164:165]
	v_pk_mul_f32 v[180:181], v[132:133], v[180:181]
	v_cvt_pk_bf16_f32 v176, v176, v177
	v_cvt_pk_bf16_f32 v177, v178, v179
	s_nop 0
	v_cvt_pk_bf16_f32 v178, v180, v181
	v_cvt_pk_bf16_f32 v179, v164, v165
	v_mad_i64_i32 v[164:165], s[50:51], s19, v203, v[158:159]
	v_lshlrev_b64 v[164:165], 8, v[164:165]
	v_lshl_add_u64 v[164:165], v[148:149], 0, v[164:165]
	global_store_dwordx4 v[164:165], v[176:179], off
	ds_read2st64_b32 v[164:165], v174 offset0:1 offset1:5
	ds_read2st64_b32 v[176:177], v174 offset0:9 offset1:13
	v_mad_i64_i32 v[158:159], s[50:51], s37, v203, v[158:159]
	v_lshlrev_b64 v[158:159], 8, v[158:159]
	s_waitcnt lgkmcnt(1)
	v_mov_b32_e32 v178, v164
	s_waitcnt lgkmcnt(0)
	v_mov_b32_e32 v179, v176
	v_mov_b32_e32 v176, v165
	v_pk_add_f32 v[164:165], v[178:179], v[176:177]
	v_lshl_add_u64 v[158:159], v[148:149], 0, v[158:159]
	v_add_f32_e32 v164, v164, v165
	v_fmamk_f32 v164, v164, 0x3c000000, v1
	v_cmp_gt_f32_e32 vcc, s33, v164
	v_mul_f32_e32 v165, 0x4b800000, v164
	s_nop 0
	v_cndmask_b32_e32 v164, v164, v165, vcc
	v_rsq_f32_e32 v164, v164
	s_nop 0
	v_mul_f32_e32 v165, 0x45800000, v164
	v_cndmask_b32_e32 v164, v164, v165, vcc
	v_pk_mul_f32 v[176:177], v[84:85], v[164:165] op_sel_hi:[1,0]
	v_pk_mul_f32 v[178:179], v[86:87], v[164:165] op_sel_hi:[1,0]
	v_pk_mul_f32 v[176:177], v[136:137], v[176:177]
	v_pk_mul_f32 v[178:179], v[138:139], v[178:179]
	v_pk_mul_f32 v[180:181], v[76:77], v[164:165] op_sel_hi:[1,0]
	v_pk_mul_f32 v[164:165], v[78:79], v[164:165] op_sel_hi:[1,0]
	v_pk_mul_f32 v[180:181], v[132:133], v[180:181]
	v_pk_mul_f32 v[164:165], v[134:135], v[164:165]
	v_cvt_pk_bf16_f32 v176, v176, v177
	v_cvt_pk_bf16_f32 v177, v178, v179
	v_cvt_pk_bf16_f32 v178, v180, v181
	s_nop 0
	v_cvt_pk_bf16_f32 v179, v164, v165
	global_store_dwordx4 v[158:159], v[176:179], off
	ds_read2st64_b32 v[164:165], v157 offset0:1 offset1:5
	ds_read2st64_b32 v[176:177], v157 offset0:9 offset1:13
	v_or_b32_e32 v158, 48, v156
	v_ashrrev_i32_e32 v159, 31, v158
	s_waitcnt lgkmcnt(1)
	v_mov_b32_e32 v178, v164
	s_waitcnt lgkmcnt(0)
	v_mov_b32_e32 v179, v176
	v_mov_b32_e32 v176, v165
	v_pk_add_f32 v[164:165], v[178:179], v[176:177]
	s_nop 0
	v_add_f32_e32 v164, v164, v165
	v_fmamk_f32 v164, v164, 0x3c000000, v1
	v_cmp_gt_f32_e32 vcc, s33, v164
	v_mul_f32_e32 v165, 0x4b800000, v164
	s_nop 0
	v_cndmask_b32_e32 v164, v164, v165, vcc
	v_rsq_f32_e32 v164, v164
	s_nop 0
	v_mul_f32_e32 v165, 0x45800000, v164
	v_cndmask_b32_e32 v164, v164, v165, vcc
	v_pk_mul_f32 v[176:177], v[88:89], v[164:165] op_sel_hi:[1,0]
	v_pk_mul_f32 v[178:179], v[90:91], v[164:165] op_sel_hi:[1,0]
	v_pk_mul_f32 v[180:181], v[80:81], v[164:165] op_sel_hi:[1,0]
	v_pk_mul_f32 v[164:165], v[82:83], v[164:165] op_sel_hi:[1,0]
	v_pk_mul_f32 v[178:179], v[138:139], v[178:179]
	v_pk_mul_f32 v[176:177], v[136:137], v[176:177]
	v_pk_mul_f32 v[164:165], v[134:135], v[164:165]
	v_pk_mul_f32 v[180:181], v[132:133], v[180:181]
	v_cvt_pk_bf16_f32 v176, v176, v177
	v_cvt_pk_bf16_f32 v177, v178, v179
	s_nop 0
	v_cvt_pk_bf16_f32 v178, v180, v181
	v_cvt_pk_bf16_f32 v179, v164, v165
	v_mad_i64_i32 v[164:165], s[50:51], s19, v203, v[158:159]
	v_lshlrev_b64 v[164:165], 8, v[164:165]
	v_lshl_add_u64 v[164:165], v[148:149], 0, v[164:165]
	global_store_dwordx4 v[164:165], v[176:179], off
	ds_read2st64_b32 v[164:165], v175 offset0:1 offset1:5
	ds_read2st64_b32 v[176:177], v175 offset0:9 offset1:13
	v_mad_i64_i32 v[158:159], s[50:51], s37, v203, v[158:159]
	v_lshlrev_b64 v[158:159], 8, v[158:159]
	s_waitcnt lgkmcnt(1)
	v_mov_b32_e32 v178, v164
	s_waitcnt lgkmcnt(0)
	v_mov_b32_e32 v179, v176
	v_mov_b32_e32 v176, v165
	v_pk_add_f32 v[164:165], v[178:179], v[176:177]
	v_lshl_add_u64 v[158:159], v[148:149], 0, v[158:159]
	v_add_f32_e32 v164, v164, v165
	v_fmamk_f32 v164, v164, 0x3c000000, v1
	v_cmp_gt_f32_e32 vcc, s33, v164
	v_mul_f32_e32 v165, 0x4b800000, v164
	s_nop 0
	v_cndmask_b32_e32 v164, v164, v165, vcc
	v_rsq_f32_e32 v164, v164
	s_nop 0
	v_mul_f32_e32 v165, 0x45800000, v164
	v_cndmask_b32_e32 v164, v164, v165, vcc
	v_pk_mul_f32 v[176:177], v[72:73], v[164:165] op_sel_hi:[1,0]
	v_pk_mul_f32 v[178:179], v[74:75], v[164:165] op_sel_hi:[1,0]
	v_pk_mul_f32 v[176:177], v[136:137], v[176:177]
	v_pk_mul_f32 v[178:179], v[138:139], v[178:179]
	v_pk_mul_f32 v[180:181], v[68:69], v[164:165] op_sel_hi:[1,0]
	v_pk_mul_f32 v[164:165], v[70:71], v[164:165] op_sel_hi:[1,0]
	v_pk_mul_f32 v[180:181], v[132:133], v[180:181]
	v_pk_mul_f32 v[164:165], v[134:135], v[164:165]
	v_cvt_pk_bf16_f32 v176, v176, v177
	v_cvt_pk_bf16_f32 v177, v178, v179
	v_cvt_pk_bf16_f32 v178, v180, v181
	s_nop 0
	v_cvt_pk_bf16_f32 v179, v164, v165
	global_store_dwordx4 v[158:159], v[176:179], off
	ds_read2st64_b32 v[164:165], v172 offset0:2 offset1:6
	ds_read2st64_b32 v[176:177], v172 offset0:10 offset1:14
	v_add_u32_e32 v158, 0x80, v156
	v_ashrrev_i32_e32 v159, 31, v158
	s_waitcnt lgkmcnt(1)
; __device__ __forceinline__ unsigned cvtpk(float lo, float hi) { unsigned r; asm volatile("v_cvt_pk_bf16_f32 %0, %1, %2" : "=v"(r) : "v"(lo), "v"(hi)); return r; }
;     __device__ __forceinline__ void operator()(const f32x4 (&acc)[2][2][4][2], const Unit& u, int wr, int wc, int fr, int fq) const {
;     ...
; #pragma unroll
;         for (int ai = 0; ai < 2; ++ai)
; #pragma unroll
;             for (int m = 0; m < 4; ++m) { const size_t r = (size_t)(row0 + ai * HALF + m * 16);
; #pragma unroll
;                 for (int bj = 0; bj < 2; ++bj) {
;                     const int slot = ((ai * 4 + m) * 2 + bj) * 16 + fr;
;                     const float tot = (xl[(wr * 4 + 0) * 256 + slot] + xl[(wr * 4 + 1) * 256 + slot]) + (xl[(wr * 4 + 2) * 256 + slot] + xl[(wr * 4 + 3) * 256 + slot]);
;                     const float rs = rsqrtf(tot * (1.f / 128) + NORM_EPS);
;                     const f32x4 v0 = acc[ai][bj][m][0] * rs * g0, v1 = acc[ai][bj][m][1] * rs * g1;
;                     u32x4 w; w.x = cvtpk(v0[0], v0[1]); w.y = cvtpk(v0[2], v0[3]); w.z = cvtpk(v1[0], v1[1]); w.w = cvtpk(v1[2], v1[3]);
;                     *(u32x4*)(base + ((size_t)(head0 + bj) * KROWS + r) * 128) = w; } }
	v_mov_b32_e32 v178, v164
	s_waitcnt lgkmcnt(0)
	v_mov_b32_e32 v179, v176
	v_mov_b32_e32 v176, v165
	v_pk_add_f32 v[164:165], v[178:179], v[176:177]
	s_nop 0
	v_add_f32_e32 v164, v164, v165
	v_fmamk_f32 v164, v164, 0x3c000000, v1
	v_cmp_gt_f32_e32 vcc, s33, v164
	v_mul_f32_e32 v165, 0x4b800000, v164
	s_nop 0
	v_cndmask_b32_e32 v164, v164, v165, vcc
	v_rsq_f32_e32 v164, v164
	s_nop 0
	v_mul_f32_e32 v165, 0x45800000, v164
	v_cndmask_b32_e32 v164, v164, v165, vcc
	v_pk_mul_f32 v[176:177], v[64:65], v[164:165] op_sel_hi:[1,0]
	v_pk_mul_f32 v[178:179], v[66:67], v[164:165] op_sel_hi:[1,0]
	v_pk_mul_f32 v[180:181], v[60:61], v[164:165] op_sel_hi:[1,0]
	v_pk_mul_f32 v[164:165], v[62:63], v[164:165] op_sel_hi:[1,0]
	v_pk_mul_f32 v[178:179], v[138:139], v[178:179]
	v_pk_mul_f32 v[176:177], v[136:137], v[176:177]
	v_pk_mul_f32 v[164:165], v[134:135], v[164:165]
	v_pk_mul_f32 v[180:181], v[132:133], v[180:181]
	v_cvt_pk_bf16_f32 v176, v176, v177
	v_cvt_pk_bf16_f32 v177, v178, v179
	s_nop 0
	v_cvt_pk_bf16_f32 v178, v180, v181
	v_cvt_pk_bf16_f32 v179, v164, v165
	v_mad_i64_i32 v[164:165], s[50:51], s19, v203, v[158:159]
	v_lshlrev_b64 v[164:165], 8, v[164:165]
	v_lshl_add_u64 v[164:165], v[148:149], 0, v[164:165]
	global_store_dwordx4 v[164:165], v[176:179], off
	ds_read2st64_b32 v[164:165], v174 offset0:2 offset1:6
	ds_read2st64_b32 v[176:177], v174 offset0:10 offset1:14
	v_mad_i64_i32 v[158:159], s[50:51], s37, v203, v[158:159]
	v_lshlrev_b64 v[158:159], 8, v[158:159]
	s_waitcnt lgkmcnt(1)
	v_mov_b32_e32 v178, v164
	s_waitcnt lgkmcnt(0)
	v_mov_b32_e32 v179, v176
	v_mov_b32_e32 v176, v165
	v_pk_add_f32 v[164:165], v[178:179], v[176:177]
	v_lshl_add_u64 v[158:159], v[148:149], 0, v[158:159]
	v_add_f32_e32 v164, v164, v165
	v_fmamk_f32 v164, v164, 0x3c000000, v1
	v_cmp_gt_f32_e32 vcc, s33, v164
	v_mul_f32_e32 v165, 0x4b800000, v164
	s_nop 0
	v_cndmask_b32_e32 v164, v164, v165, vcc
	v_rsq_f32_e32 v164, v164
	s_nop 0
	v_mul_f32_e32 v165, 0x45800000, v164
	v_cndmask_b32_e32 v164, v164, v165, vcc
	v_pk_mul_f32 v[176:177], v[52:53], v[164:165] op_sel_hi:[1,0]
	v_pk_mul_f32 v[178:179], v[54:55], v[164:165] op_sel_hi:[1,0]
	v_pk_mul_f32 v[176:177], v[136:137], v[176:177]
	v_pk_mul_f32 v[178:179], v[138:139], v[178:179]
	v_pk_mul_f32 v[180:181], v[44:45], v[164:165] op_sel_hi:[1,0]
	v_pk_mul_f32 v[164:165], v[46:47], v[164:165] op_sel_hi:[1,0]
	v_pk_mul_f32 v[180:181], v[132:133], v[180:181]
	v_pk_mul_f32 v[164:165], v[134:135], v[164:165]
	v_cvt_pk_bf16_f32 v176, v176, v177
	v_cvt_pk_bf16_f32 v177, v178, v179
	v_cvt_pk_bf16_f32 v178, v180, v181
	s_nop 0
	v_cvt_pk_bf16_f32 v179, v164, v165
	global_store_dwordx4 v[158:159], v[176:179], off
	ds_read2st64_b32 v[164:165], v157 offset0:2 offset1:6
	ds_read2st64_b32 v[176:177], v157 offset0:10 offset1:14
	v_add_u32_e32 v158, 0x90, v156
	v_ashrrev_i32_e32 v159, 31, v158
	s_waitcnt lgkmcnt(1)
	v_mov_b32_e32 v178, v164
	s_waitcnt lgkmcnt(0)
	v_mov_b32_e32 v179, v176
	v_mov_b32_e32 v176, v165
	v_pk_add_f32 v[164:165], v[178:179], v[176:177]
	s_nop 0
	v_add_f32_e32 v164, v164, v165
	v_fmamk_f32 v164, v164, 0x3c000000, v1
	v_cmp_gt_f32_e32 vcc, s33, v164
	v_mul_f32_e32 v165, 0x4b800000, v164
	s_nop 0
	v_cndmask_b32_e32 v164, v164, v165, vcc
	v_rsq_f32_e32 v164, v164
	s_nop 0
	v_mul_f32_e32 v165, 0x45800000, v164
	v_cndmask_b32_e32 v164, v164, v165, vcc
	v_pk_mul_f32 v[176:177], v[56:57], v[164:165] op_sel_hi:[1,0]
	v_pk_mul_f32 v[178:179], v[58:59], v[164:165] op_sel_hi:[1,0]
	v_pk_mul_f32 v[180:181], v[48:49], v[164:165] op_sel_hi:[1,0]
	v_pk_mul_f32 v[164:165], v[50:51], v[164:165] op_sel_hi:[1,0]
	v_pk_mul_f32 v[178:179], v[138:139], v[178:179]
	v_pk_mul_f32 v[176:177], v[136:137], v[176:177]
	v_pk_mul_f32 v[164:165], v[134:135], v[164:165]
	v_pk_mul_f32 v[180:181], v[132:133], v[180:181]
	v_cvt_pk_bf16_f32 v176, v176, v177
	v_cvt_pk_bf16_f32 v177, v178, v179
	s_nop 0
	v_cvt_pk_bf16_f32 v178, v180, v181
	v_cvt_pk_bf16_f32 v179, v164, v165
	v_mad_i64_i32 v[164:165], s[50:51], s19, v203, v[158:159]
	v_lshlrev_b64 v[164:165], 8, v[164:165]
	v_lshl_add_u64 v[164:165], v[148:149], 0, v[164:165]
	global_store_dwordx4 v[164:165], v[176:179], off
	ds_read2st64_b32 v[164:165], v175 offset0:2 offset1:6
	ds_read2st64_b32 v[176:177], v175 offset0:10 offset1:14
	v_mad_i64_i32 v[158:159], s[50:51], s37, v203, v[158:159]
	v_lshlrev_b64 v[158:159], 8, v[158:159]
	s_waitcnt lgkmcnt(1)
	v_mov_b32_e32 v178, v164
	s_waitcnt lgkmcnt(0)
	v_mov_b32_e32 v179, v176
	v_mov_b32_e32 v176, v165
	v_pk_add_f32 v[164:165], v[178:179], v[176:177]
	v_lshl_add_u64 v[158:159], v[148:149], 0, v[158:159]
	v_add_f32_e32 v164, v164, v165
	v_fmamk_f32 v164, v164, 0x3c000000, v1
	v_cmp_gt_f32_e32 vcc, s33, v164
	v_mul_f32_e32 v165, 0x4b800000, v164
	s_nop 0
	v_cndmask_b32_e32 v164, v164, v165, vcc
	v_rsq_f32_e32 v164, v164
	s_nop 0
	v_mul_f32_e32 v165, 0x45800000, v164
	v_cndmask_b32_e32 v164, v164, v165, vcc
	v_pk_mul_f32 v[176:177], v[36:37], v[164:165] op_sel_hi:[1,0]
	v_pk_mul_f32 v[178:179], v[38:39], v[164:165] op_sel_hi:[1,0]
	v_pk_mul_f32 v[176:177], v[136:137], v[176:177]
	v_pk_mul_f32 v[178:179], v[138:139], v[178:179]
	v_pk_mul_f32 v[180:181], v[28:29], v[164:165] op_sel_hi:[1,0]
	v_pk_mul_f32 v[164:165], v[30:31], v[164:165] op_sel_hi:[1,0]
	v_pk_mul_f32 v[180:181], v[132:133], v[180:181]
	v_pk_mul_f32 v[164:165], v[134:135], v[164:165]
	v_cvt_pk_bf16_f32 v176, v176, v177
	v_cvt_pk_bf16_f32 v177, v178, v179
	v_cvt_pk_bf16_f32 v178, v180, v181
	s_nop 0
	v_cvt_pk_bf16_f32 v179, v164, v165
	global_store_dwordx4 v[158:159], v[176:179], off
	ds_read2st64_b32 v[164:165], v172 offset0:3 offset1:7
	ds_read2st64_b32 v[176:177], v172 offset0:11 offset1:15
	v_add_u32_e32 v158, 0xa0, v156
	v_ashrrev_i32_e32 v159, 31, v158
	s_waitcnt lgkmcnt(1)
; __device__ __forceinline__ unsigned cvtpk(float lo, float hi) { unsigned r; asm volatile("v_cvt_pk_bf16_f32 %0, %1, %2" : "=v"(r) : "v"(lo), "v"(hi)); return r; }
;     __device__ __forceinline__ void operator()(const f32x4 (&acc)[2][2][4][2], const Unit& u, int wr, int wc, int fr, int fq) const {
;     ...
; #pragma unroll
;         for (int ai = 0; ai < 2; ++ai)
; #pragma unroll
;             for (int m = 0; m < 4; ++m) { const size_t r = (size_t)(row0 + ai * HALF + m * 16);
; #pragma unroll
;                 for (int bj = 0; bj < 2; ++bj) {
;                     const int slot = ((ai * 4 + m) * 2 + bj) * 16 + fr;
;                     const float tot = (xl[(wr * 4 + 0) * 256 + slot] + xl[(wr * 4 + 1) * 256 + slot]) + (xl[(wr * 4 + 2) * 256 + slot] + xl[(wr * 4 + 3) * 256 + slot]);
;                     const float rs = rsqrtf(tot * (1.f / 128) + NORM_EPS);
;                     const f32x4 v0 = acc[ai][bj][m][0] * rs * g0, v1 = acc[ai][bj][m][1] * rs * g1;
;                     u32x4 w; w.x = cvtpk(v0[0], v0[1]); w.y = cvtpk(v0[2], v0[3]); w.z = cvtpk(v1[0], v1[1]); w.w = cvtpk(v1[2], v1[3]);
;                     *(u32x4*)(base + ((size_t)(head0 + bj) * KROWS + r) * 128) = w; } }
	v_mov_b32_e32 v178, v164
	s_waitcnt lgkmcnt(0)
	v_mov_b32_e32 v179, v176
	v_mov_b32_e32 v176, v165
	v_pk_add_f32 v[164:165], v[178:179], v[176:177]
	s_nop 0
	v_add_f32_e32 v164, v164, v165
	v_fmamk_f32 v164, v164, 0x3c000000, v1
	v_cmp_gt_f32_e32 vcc, s33, v164
	v_mul_f32_e32 v165, 0x4b800000, v164
	s_nop 0
	v_cndmask_b32_e32 v164, v164, v165, vcc
	v_rsq_f32_e32 v164, v164
	s_nop 0
	v_mul_f32_e32 v165, 0x45800000, v164
	v_cndmask_b32_e32 v164, v164, v165, vcc
	v_pk_mul_f32 v[176:177], v[40:41], v[164:165] op_sel_hi:[1,0]
	v_pk_mul_f32 v[178:179], v[42:43], v[164:165] op_sel_hi:[1,0]
	v_pk_mul_f32 v[180:181], v[32:33], v[164:165] op_sel_hi:[1,0]
	v_pk_mul_f32 v[164:165], v[34:35], v[164:165] op_sel_hi:[1,0]
	v_pk_mul_f32 v[178:179], v[138:139], v[178:179]
	v_pk_mul_f32 v[176:177], v[136:137], v[176:177]
	v_pk_mul_f32 v[164:165], v[134:135], v[164:165]
	v_pk_mul_f32 v[180:181], v[132:133], v[180:181]
	v_cvt_pk_bf16_f32 v176, v176, v177
	v_cvt_pk_bf16_f32 v177, v178, v179
	s_nop 0
	v_cvt_pk_bf16_f32 v178, v180, v181
	v_cvt_pk_bf16_f32 v179, v164, v165
	v_mad_i64_i32 v[164:165], s[50:51], s19, v203, v[158:159]
	v_lshlrev_b64 v[164:165], 8, v[164:165]
	v_lshl_add_u64 v[164:165], v[148:149], 0, v[164:165]
	global_store_dwordx4 v[164:165], v[176:179], off
	ds_read2st64_b32 v[164:165], v174 offset0:3 offset1:7
	ds_read2st64_b32 v[176:177], v174 offset0:11 offset1:15
	v_mad_i64_i32 v[158:159], s[50:51], s37, v203, v[158:159]
	v_lshlrev_b64 v[158:159], 8, v[158:159]
	s_waitcnt lgkmcnt(1)
	v_mov_b32_e32 v178, v164
	s_waitcnt lgkmcnt(0)
	v_mov_b32_e32 v179, v176
	v_mov_b32_e32 v176, v165
	v_pk_add_f32 v[164:165], v[178:179], v[176:177]
	v_lshl_add_u64 v[158:159], v[148:149], 0, v[158:159]
	v_add_f32_e32 v164, v164, v165
	v_fmamk_f32 v164, v164, 0x3c000000, v1
	v_cmp_gt_f32_e32 vcc, s33, v164
	v_mul_f32_e32 v165, 0x4b800000, v164
	s_nop 0
	v_cndmask_b32_e32 v164, v164, v165, vcc
	v_rsq_f32_e32 v164, v164
	s_nop 0
	v_mul_f32_e32 v165, 0x45800000, v164
	v_cndmask_b32_e32 v164, v164, v165, vcc
	v_pk_mul_f32 v[176:177], v[20:21], v[164:165] op_sel_hi:[1,0]
	v_pk_mul_f32 v[178:179], v[22:23], v[164:165] op_sel_hi:[1,0]
	v_pk_mul_f32 v[176:177], v[136:137], v[176:177]
	v_pk_mul_f32 v[178:179], v[138:139], v[178:179]
	v_pk_mul_f32 v[180:181], v[12:13], v[164:165] op_sel_hi:[1,0]
	v_pk_mul_f32 v[164:165], v[14:15], v[164:165] op_sel_hi:[1,0]
	v_pk_mul_f32 v[180:181], v[132:133], v[180:181]
	v_pk_mul_f32 v[164:165], v[134:135], v[164:165]
	v_cvt_pk_bf16_f32 v176, v176, v177
	v_cvt_pk_bf16_f32 v177, v178, v179
	v_cvt_pk_bf16_f32 v178, v180, v181
	s_nop 0
	v_cvt_pk_bf16_f32 v179, v164, v165
	global_store_dwordx4 v[158:159], v[176:179], off
	ds_read2st64_b32 v[164:165], v157 offset0:3 offset1:7
	ds_read2st64_b32 v[176:177], v157 offset0:11 offset1:15
	v_add_u32_e32 v158, 0xb0, v156
	v_ashrrev_i32_e32 v159, 31, v158
	s_waitcnt lgkmcnt(1)
	v_mov_b32_e32 v178, v164
	s_waitcnt lgkmcnt(0)
	v_mov_b32_e32 v179, v176
	v_mov_b32_e32 v176, v165
	v_pk_add_f32 v[164:165], v[178:179], v[176:177]
	s_nop 0
	v_add_f32_e32 v157, v164, v165
	v_fmamk_f32 v157, v157, 0x3c000000, v1
	v_cmp_gt_f32_e32 vcc, s33, v157
	v_mul_f32_e32 v164, 0x4b800000, v157
	s_nop 0
	v_cndmask_b32_e32 v157, v157, v164, vcc
	v_rsq_f32_e32 v157, v157
	s_nop 0
	v_mul_f32_e32 v164, 0x45800000, v157
	v_cndmask_b32_e32 v164, v157, v164, vcc
	v_pk_mul_f32 v[176:177], v[24:25], v[164:165] op_sel_hi:[1,0]
	v_pk_mul_f32 v[178:179], v[26:27], v[164:165] op_sel_hi:[1,0]
	v_pk_mul_f32 v[180:181], v[16:17], v[164:165] op_sel_hi:[1,0]
	v_pk_mul_f32 v[164:165], v[18:19], v[164:165] op_sel_hi:[1,0]
	v_pk_mul_f32 v[178:179], v[138:139], v[178:179]
	v_pk_mul_f32 v[176:177], v[136:137], v[176:177]
	v_pk_mul_f32 v[164:165], v[134:135], v[164:165]
	v_pk_mul_f32 v[180:181], v[132:133], v[180:181]
	v_cvt_pk_bf16_f32 v176, v176, v177
	v_cvt_pk_bf16_f32 v177, v178, v179
	s_nop 0
	v_cvt_pk_bf16_f32 v178, v180, v181
	v_cvt_pk_bf16_f32 v179, v164, v165
	v_mad_i64_i32 v[164:165], s[50:51], s19, v203, v[158:159]
	v_lshlrev_b64 v[164:165], 8, v[164:165]
	v_lshl_add_u64 v[164:165], v[148:149], 0, v[164:165]
	global_store_dwordx4 v[164:165], v[176:179], off
	ds_read2st64_b32 v[164:165], v175 offset0:3 offset1:7
	ds_read2st64_b32 v[174:175], v175 offset0:11 offset1:15
	s_waitcnt lgkmcnt(1)
	v_mov_b32_e32 v176, v164
	s_waitcnt lgkmcnt(0)
	v_mov_b32_e32 v177, v174
	v_mov_b32_e32 v174, v165
	v_pk_add_f32 v[164:165], v[176:177], v[174:175]
	s_nop 0
	v_add_f32_e32 v157, v164, v165
	v_fmamk_f32 v157, v157, 0x3c000000, v1
	v_cmp_gt_f32_e32 vcc, s33, v157
	v_mul_f32_e32 v164, 0x4b800000, v157
	s_nop 0
	v_cndmask_b32_e32 v157, v157, v164, vcc
	v_rsq_f32_e32 v157, v157
	s_nop 0
	v_mul_f32_e32 v164, 0x45800000, v157
	v_cndmask_b32_e32 v164, v157, v164, vcc
	v_pk_mul_f32 v[174:175], v[8:9], v[164:165] op_sel_hi:[1,0]
	v_pk_mul_f32 v[176:177], v[10:11], v[164:165] op_sel_hi:[1,0]
	v_pk_mul_f32 v[136:137], v[136:137], v[174:175]
	v_pk_mul_f32 v[174:175], v[4:5], v[164:165] op_sel_hi:[1,0]
	v_pk_mul_f32 v[164:165], v[6:7], v[164:165] op_sel_hi:[1,0]
	v_pk_mul_f32 v[138:139], v[138:139], v[176:177]
	v_pk_mul_f32 v[164:165], v[134:135], v[164:165]
	v_pk_mul_f32 v[134:135], v[132:133], v[174:175]
	v_cvt_pk_bf16_f32 v132, v136, v137
	v_mad_i64_i32 v[136:137], s[50:51], s37, v203, v[158:159]
	v_cvt_pk_bf16_f32 v133, v138, v139
	v_cvt_pk_bf16_f32 v134, v134, v135
	v_cvt_pk_bf16_f32 v135, v164, v165
	v_mov_b64_e32 v[138:139], v[148:149]
	s_branch .LBB0_803
